# last-layer f32 output norm loop: gain vectors register-resident (no reload behind vmcnt(0) after every store)
# speedup vs baseline: 1.0011x; 1.0011x over previous
; DI float bflo(unsigned w) { return __uint_as_float(w << 16); }
; DI float bfhi(unsigned w) { return __uint_as_float(w & 0xffff0000u); }
; template <bool XOUT_BF, int NR>
; DI void norm_rows(const bf16_t* xin, const bf16_t* Rb, const float* gpost, void* xout, const float* gpre, bf16_t* xnb, size_t row0, size_t rstride, int lane) {
;     f32x4 v[NR][4], r[NR][4];
; #pragma unroll
;     for (int q = 0; q < NR; ++q)
; #pragma unroll
;         for (int j = 0; j < 4; ++j) { const size_t off = (row0 + q * rstride) * D + 4 * lane + 256 * j;
;             const u32x2 w = __builtin_nontemporal_load((const u32x2*)(xin + off)); v[q][j] = (f32x4){bflo(w.x), bfhi(w.x), bflo(w.y), bfhi(w.y)};
;             const u32x2 w2 = __builtin_nontemporal_load((const u32x2*)(Rb + off)); r[q][j] = (f32x4){bflo(w2.x), bfhi(w2.x), bflo(w2.y), bfhi(w2.y)}; }
;     float ss[NR], s2[NR];
; #pragma unroll
;     for (int q = 0; q < NR; ++q) { ss[q] = 0.f; s2[q] = 0.f;
; #pragma unroll
;         for (int j = 0; j < 4; ++j) ss[q] += (r[q][j][0] * r[q][j][0] + r[q][j][1] * r[q][j][1]) + (r[q][j][2] * r[q][j][2] + r[q][j][3] * r[q][j][3]); }
; #pragma unroll
;     for (int o = 1; o < 64; o <<= 1)
; #pragma unroll
;         for (int q = 0; q < NR; ++q) ss[q] += __shfl_xor(ss[q], o);
.LBB0_1590:
	s_andn2_b64 vcc, exec, s[50:51]
	s_mov_b64 s[52:53], 0x4000000
	s_brev_b32 s42, 32
	s_cbranch_vccnz .LBB0_1594
	s_and_b64 vcc, exec, s[2:3]
	s_cbranch_vccnz .LBB0_1594
	v_lshlrev_b32_e32 v176, 4, v110
	s_waitcnt lgkmcnt(0)
	v_lshl_add_u64 v[0:1], s[16:17], 0, v[176:177]
	s_mov_b64 s[2:3], 0x3000
	s_ashr_i32 s37, s36, 31
	s_ashr_i32 s39, s38, 31
	v_lshl_add_u64 v[0:1], v[0:1], 0, s[2:3]
	global_load_dwordx4 v[140:143], v[0:1], off
	global_load_dwordx4 v[144:147], v[0:1], off offset:1024
	global_load_dwordx4 v[148:151], v[0:1], off offset:2048
	global_load_dwordx4 v[152:155], v[0:1], off offset:3072
	s_lshl_b32 s2, s33, 5
	s_lshl_b64 s[4:5], s[36:37], 12
	s_add_u32 s4, s22, s4
	s_addc_u32 s5, s23, s5
	s_ashr_i32 s3, s2, 31
	v_lshl_add_u64 v[2:3], s[4:5], 0, v[176:177]
	s_lshl_b64 s[4:5], s[2:3], 12
	s_lshl_b64 s[16:17], s[36:37], 11
	s_add_u32 s16, s34, s16
	v_lshlrev_b32_e32 v176, 3, v110
	s_addc_u32 s17, s35, s17
	v_lshl_add_u64 v[4:5], s[16:17], 0, v[176:177]
	s_mov_b64 s[16:17], 0x3d00000
	v_lshl_add_u64 v[4:5], v[4:5], 0, s[16:17]
	s_lshl_b64 s[16:17], s[2:3], 11
	s_lshl_b64 s[22:23], s[38:39], 11
	s_add_u32 s22, s22, 0xfc000000
	s_addc_u32 s23, s23, -1
	s_lshl_b64 s[50:51], s[38:39], 12
	s_mov_b32 s3, s36
.LBB0_1593:
	s_waitcnt vmcnt(16)
	s_nop 0
	v_add_co_u32_e32 v6, vcc, 0x4000000, v4
	v_lshl_add_u64 v[8:9], v[4:5], 0, s[52:53]
	s_nop 0
	v_addc_co_u32_e32 v7, vcc, 0, v5, vcc
	global_load_dwordx2 v[32:33], v[4:5], off nt
	global_load_dwordx2 v[20:21], v[4:5], off offset:512 nt
	global_load_dwordx2 v[14:15], v[4:5], off offset:1024 nt
	global_load_dwordx2 v[12:13], v[4:5], off offset:1536 nt
	global_load_dwordx2 v[58:59], v[8:9], off offset:512 nt
	global_load_dwordx2 v[60:61], v[8:9], off offset:1024 nt
	global_load_dwordx2 v[62:63], v[8:9], off offset:1536 nt
	global_load_dwordx2 v[64:65], v[6:7], off nt
	v_lshl_add_u64 v[8:9], v[8:9], 0, s[22:23]
	v_lshl_add_u64 v[6:7], v[8:9], 0, s[52:53]
	global_load_dwordx2 v[66:67], v[8:9], off nt
	global_load_dwordx2 v[52:53], v[8:9], off offset:512 nt
	global_load_dwordx2 v[50:51], v[8:9], off offset:1024 nt
	global_load_dwordx2 v[38:39], v[8:9], off offset:1536 nt
	v_add_co_u32_e32 v8, vcc, s42, v8
	v_lshl_add_u64 v[10:11], v[6:7], 0, s[22:23]
	s_nop 0
	v_addc_co_u32_e32 v9, vcc, 0, v9, vcc
	global_load_dwordx2 v[68:69], v[6:7], off offset:512 nt
	global_load_dwordx2 v[70:71], v[6:7], off offset:1024 nt
	global_load_dwordx2 v[72:73], v[6:7], off offset:1536 nt
	global_load_dwordx2 v[74:75], v[8:9], off nt
	v_lshl_add_u64 v[6:7], v[10:11], 0, s[52:53]
	v_add_co_u32_e32 v8, vcc, s42, v10
	v_lshl_add_u64 v[16:17], v[6:7], 0, s[22:23]
	s_nop 0
	v_addc_co_u32_e32 v9, vcc, 0, v11, vcc
	global_load_dwordx2 v[44:45], v[10:11], off nt
	global_load_dwordx2 v[34:35], v[10:11], off offset:512 nt
	global_load_dwordx2 v[30:31], v[10:11], off offset:1024 nt
	global_load_dwordx2 v[24:25], v[10:11], off offset:1536 nt
	global_load_dwordx2 v[42:43], v[6:7], off offset:512 nt
	global_load_dwordx2 v[40:41], v[6:7], off offset:1024 nt
	global_load_dwordx2 v[46:47], v[6:7], off offset:1536 nt
	global_load_dwordx2 v[36:37], v[8:9], off nt
	v_lshl_add_u64 v[28:29], v[16:17], 0, s[52:53]
	global_load_dwordx2 v[26:27], v[16:17], off nt
	global_load_dwordx2 v[10:11], v[16:17], off offset:512 nt
	global_load_dwordx2 v[8:9], v[16:17], off offset:1024 nt
	global_load_dwordx2 v[6:7], v[16:17], off offset:1536 nt
	v_add_co_u32_e32 v16, vcc, s42, v16
	s_add_i32 s3, s3, s2
	s_nop 0
	v_addc_co_u32_e32 v17, vcc, 0, v17, vcc
	global_load_dwordx2 v[22:23], v[28:29], off offset:512 nt
	global_load_dwordx2 v[18:19], v[28:29], off offset:1024 nt
	s_nop 0
	global_load_dwordx2 v[28:29], v[28:29], off offset:1536 nt
	s_nop 0
	global_load_dwordx2 v[16:17], v[16:17], off nt
	s_cmpk_gt_i32 s3, 0x7fff
	v_lshl_add_u64 v[4:5], v[4:5], 0, s[16:17]
	s_waitcnt vmcnt(0)
	v_mov_b32_e32 v54, v140
	v_mov_b32_e32 v55, v141
	v_mov_b32_e32 v56, v142
	v_mov_b32_e32 v57, v143
	v_lshlrev_b32_e32 v76, 16, v32
	v_and_b32_e32 v77, 0xffff0000, v32
	v_lshlrev_b32_e32 v32, 16, v33
	v_and_b32_e32 v33, 0xffff0000, v33
	v_lshlrev_b32_e32 v79, 16, v59
	v_lshlrev_b32_e32 v80, 16, v60
	v_and_b32_e32 v81, 0xffff0000, v60
	v_lshlrev_b32_e32 v60, 16, v61
	v_and_b32_e32 v61, 0xffff0000, v61
	v_lshlrev_b32_e32 v83, 16, v62
	v_and_b32_e32 v85, 0xffff0000, v62
	v_lshlrev_b32_e32 v62, 16, v63
	v_and_b32_e32 v63, 0xffff0000, v63
	v_mul_f32_e32 v82, v81, v81
	v_mul_f32_e32 v84, v61, v61
	v_lshlrev_b32_e32 v90, 16, v64
	v_and_b32_e32 v91, 0xffff0000, v64
	v_lshlrev_b32_e32 v64, 16, v65
	v_and_b32_e32 v65, 0xffff0000, v65
	v_lshlrev_b32_e32 v78, 16, v58
	v_and_b32_e32 v59, 0xffff0000, v59
	v_and_b32_e32 v58, 0xffff0000, v58
	v_mul_f32_e32 v96, v63, v63
	v_pk_fma_f32 v[92:93], v[80:81], v[80:81], v[82:83] op_sel_hi:[1,1,0]
	v_pk_fma_f32 v[94:95], v[60:61], v[60:61], v[84:85] op_sel_hi:[1,1,0]
	v_mul_f32_e32 v82, v65, v65
	v_mul_f32_e32 v84, v91, v91
	v_pk_mul_f32 v[86:87], v[58:59], v[58:59]
	v_mul_f32_e32 v88, v62, v62
	v_mov_b32_e32 v95, v96
	v_pk_fma_f32 v[96:97], v[64:65], v[64:65], v[82:83] op_sel_hi:[1,1,0]
	v_pk_fma_f32 v[98:99], v[90:91], v[90:91], v[84:85] op_sel_hi:[1,1,0]
	v_mov_b32_e32 v89, v83
	v_pk_fma_f32 v[86:87], v[78:79], v[78:79], v[86:87]
	v_mov_b32_e32 v93, v88
	v_mov_b32_e32 v82, v98
	v_mov_b32_e32 v88, v96
	v_mul_f32_e32 v49, v85, v85
	v_pk_add_f32 v[86:87], v[86:87], v[86:87] op_sel:[0,1] op_sel_hi:[1,0]
	v_pk_add_f32 v[92:93], v[92:93], v[94:95]
	v_pk_add_f32 v[94:95], v[98:99], v[96:97]
	v_pk_mul_f32 v[88:89], v[82:83], v[88:89]
	v_mov_b32_e32 v87, v49
	v_mov_b32_e32 v95, v89
	v_pk_add_f32 v[86:87], v[94:95], v[86:87]
	v_mov_b32_e32 v84, v83
	v_pk_add_f32 v[86:87], v[86:87], v[92:93]
	s_nop 0
	v_add_f32_e32 v49, v86, v87
	ds_bpermute_b32 v82, v206, v49
	s_waitcnt lgkmcnt(0)
; DI unsigned cvt_pk_bf16(float lo, float hi) { const f32x2 v = {lo, hi}; return __builtin_bit_cast(unsigned, __builtin_convertvector(v, bf16x2_t)); }
; DI float bflo(unsigned w) { return __uint_as_float(w << 16); }
; DI float bfhi(unsigned w) { return __uint_as_float(w & 0xffff0000u); }
; template <bool XOUT_BF, int NR>
; DI void norm_rows(const bf16_t* xin, const bf16_t* Rb, const float* gpost, void* xout, const float* gpre, bf16_t* xnb, size_t row0, size_t rstride, int lane) {
;     ...
;         for (int j = 0; j < 4; ++j) { const size_t off = (row0 + q * rstride) * D + 4 * lane + 256 * j;
;             const u32x2 w = __builtin_nontemporal_load((const u32x2*)(xin + off)); v[q][j] = (f32x4){bflo(w.x), bfhi(w.x), bflo(w.y), bfhi(w.y)};
;             const u32x2 w2 = __builtin_nontemporal_load((const u32x2*)(Rb + off)); r[q][j] = (f32x4){bflo(w2.x), bfhi(w2.x), bflo(w2.y), bfhi(w2.y)}; }
;     float ss[NR], s2[NR];
; #pragma unroll
;     for (int q = 0; q < NR; ++q) { ss[q] = 0.f; s2[q] = 0.f;
; #pragma unroll
;         for (int j = 0; j < 4; ++j) ss[q] += (r[q][j][0] * r[q][j][0] + r[q][j][1] * r[q][j][1]) + (r[q][j][2] * r[q][j][2] + r[q][j][3] * r[q][j][3]); }
; #pragma unroll
;     for (int o = 1; o < 64; o <<= 1)
; #pragma unroll
;         for (int q = 0; q < NR; ++q) ss[q] += __shfl_xor(ss[q], o);
; #pragma unroll
;     for (int q = 0; q < NR; ++q) { const float rinv = __builtin_amdgcn_rsqf(ss[q] * (1.f / 1024.f) + EPS);
; #pragma unroll
;         for (int j = 0; j < 4; ++j) { const size_t off = (row0 + q * rstride) * D + 4 * lane + 256 * j;
;             const f32x4 g = *(const f32x4*)(gpost + 4 * lane + 256 * j); v[q][j] += r[q][j] * rinv * g;
;             if (XOUT_BF) { u32x2 w; w.x = cvt_pk_bf16(v[q][j][0], v[q][j][1]); w.y = cvt_pk_bf16(v[q][j][2], v[q][j][3]); __builtin_nontemporal_store(w, (u32x2*)((bf16_t*)xout + off));
;                            v[q][j] = (f32x4){bflo(w.x), bfhi(w.x), bflo(w.y), bfhi(w.y)}; }
;             else *(f32x4*)((float*)xout + off) = v[q][j];
;             s2[q] += (v[q][j][0] * v[q][j][0] + v[q][j][1] * v[q][j][1]) + (v[q][j][2] * v[q][j][2] + v[q][j][3] * v[q][j][3]); } }
	v_add_f32_e32 v49, v49, v82
	ds_bpermute_b32 v82, v207, v49
	s_waitcnt lgkmcnt(0)
	v_add_f32_e32 v49, v49, v82
	ds_bpermute_b32 v82, v208, v49
	s_waitcnt lgkmcnt(0)
	v_add_f32_e32 v49, v49, v82
	ds_bpermute_b32 v82, v209, v49
	s_waitcnt lgkmcnt(0)
	v_add_f32_e32 v49, v49, v82
	ds_bpermute_b32 v82, v210, v49
	s_waitcnt lgkmcnt(0)
	v_add_f32_e32 v49, v49, v82
	ds_bpermute_b32 v82, v211, v49
	s_waitcnt lgkmcnt(0)
	v_add_f32_e32 v49, v49, v82
	v_fmamk_f32 v49, v49, 0x3a800000, v217
	v_rsq_f32_e32 v82, v49
	s_nop 0
	v_pk_mul_f32 v[86:87], v[82:83], v[90:91] op_sel_hi:[0,1]
	v_pk_mul_f32 v[64:65], v[82:83], v[64:65] op_sel_hi:[0,1]
	v_pk_fma_f32 v[56:57], v[56:57], v[64:65], v[32:33]
	v_pk_fma_f32 v[54:55], v[54:55], v[86:87], v[76:77]
	global_store_dwordx4 v[2:3], v[54:57], off
	v_mov_b32_e32 v64, v79
	v_mov_b32_e32 v65, v59
	v_mov_b32_e32 v79, v58
	v_lshlrev_b32_e32 v32, 16, v20
	v_and_b32_e32 v33, 0xffff0000, v20
	v_lshlrev_b32_e32 v20, 16, v21
	v_and_b32_e32 v21, 0xffff0000, v21
	v_pk_mul_f32 v[58:59], v[82:83], v[64:65] op_sel_hi:[0,1]
	v_pk_mul_f32 v[64:65], v[82:83], v[78:79] op_sel_hi:[0,1]
	v_pk_mul_f32 v[62:63], v[82:83], v[62:63] op_sel_hi:[0,1]
	v_and_b32_e32 v79, 0xffff0000, v70
	v_lshlrev_b32_e32 v77, 16, v69
	v_lshlrev_b32_e32 v76, 16, v68
	v_and_b32_e32 v69, 0xffff0000, v69
	v_and_b32_e32 v68, 0xffff0000, v68
	v_lshlrev_b32_e32 v78, 16, v70
	v_lshlrev_b32_e32 v70, 16, v71
	v_and_b32_e32 v71, 0xffff0000, v71
	v_pk_mul_f32 v[86:87], v[68:69], v[68:69]
	s_nop 0
	v_mov_b32_e32 v54, v144
	v_mov_b32_e32 v55, v145
	v_mov_b32_e32 v56, v146
	v_mov_b32_e32 v57, v147
	v_pk_fma_f32 v[54:55], v[54:55], v[64:65], v[32:33]
	v_pk_fma_f32 v[56:57], v[56:57], v[58:59], v[20:21]
	global_store_dwordx4 v[2:3], v[54:57], off offset:1024
	v_lshlrev_b32_e32 v20, 16, v14
	v_and_b32_e32 v21, 0xffff0000, v14
	v_lshlrev_b32_e32 v14, 16, v15
	v_and_b32_e32 v15, 0xffff0000, v15
	v_pk_mul_f32 v[32:33], v[82:83], v[60:61] op_sel_hi:[0,1]
	v_pk_mul_f32 v[58:59], v[82:83], v[80:81] op_sel_hi:[0,1]
	v_lshlrev_b32_e32 v65, 16, v72
	v_lshlrev_b32_e32 v80, 16, v74
	v_and_b32_e32 v81, 0xffff0000, v74
	v_lshlrev_b32_e32 v74, 16, v75
	v_and_b32_e32 v75, 0xffff0000, v75
	v_lshlrev_b32_e32 v60, 16, v67
	v_and_b32_e32 v61, 0xffff0000, v67
	v_and_b32_e32 v67, 0xffff0000, v72
	v_lshlrev_b32_e32 v72, 16, v73
	v_mul_f32_e32 v64, v72, v72
	v_and_b32_e32 v73, 0xffff0000, v73
	v_mul_f32_e32 v49, v67, v67
	s_nop 0
	v_mov_b32_e32 v54, v148
	v_mov_b32_e32 v55, v149
	v_mov_b32_e32 v56, v150
	v_mov_b32_e32 v57, v151
	v_pk_fma_f32 v[54:55], v[54:55], v[58:59], v[20:21]
	v_pk_fma_f32 v[56:57], v[56:57], v[32:33], v[14:15]
	global_store_dwordx4 v[2:3], v[54:57], off offset:2048
	v_lshlrev_b32_e32 v14, 16, v12
	v_and_b32_e32 v15, 0xffff0000, v12
	v_lshlrev_b32_e32 v32, 16, v13
	v_and_b32_e32 v33, 0xffff0000, v13
	v_pk_mul_f32 v[12:13], v[82:83], v[84:85] op_sel_hi:[0,1]
	v_pk_fma_f32 v[82:83], v[76:77], v[76:77], v[86:87]
	v_lshlrev_b32_e32 v58, 16, v66
	v_and_b32_e32 v59, 0xffff0000, v66
	v_mul_f32_e32 v66, v73, v73
	v_pk_add_f32 v[82:83], v[82:83], v[82:83] op_sel:[0,1] op_sel_hi:[1,0]
	v_lshl_add_u64 v[20:21], v[2:3], 0, s[50:51]
	v_mov_b32_e32 v83, v49
	s_nop 0
	v_mov_b32_e32 v54, v152
	v_mov_b32_e32 v55, v153
	v_mov_b32_e32 v56, v154
	v_mov_b32_e32 v57, v155
	v_pk_fma_f32 v[12:13], v[12:13], v[54:55], v[14:15]
	v_pk_fma_f32 v[14:15], v[62:63], v[56:57], v[32:33]
	global_store_dwordx4 v[2:3], v[12:15], off offset:3072
	v_mov_b32_e32 v33, v65
	v_mul_f32_e32 v32, v79, v79
	v_mul_f32_e32 v56, v75, v75
	v_mul_f32_e32 v62, v81, v81
	v_pk_fma_f32 v[84:85], v[78:79], v[78:79], v[32:33] op_sel_hi:[1,1,0]
	v_pk_fma_f32 v[56:57], v[74:75], v[74:75], v[56:57] op_sel_hi:[1,1,0]
	v_pk_fma_f32 v[62:63], v[80:81], v[80:81], v[62:63] op_sel_hi:[1,1,0]
	v_mul_f32_e32 v54, v71, v71
	v_mov_b32_e32 v85, v64
	v_mov_b32_e32 v64, v62
	v_mov_b32_e32 v32, v56
	v_pk_fma_f32 v[54:55], v[70:71], v[70:71], v[54:55] op_sel_hi:[1,1,0]
	v_pk_add_f32 v[56:57], v[62:63], v[56:57]
	v_pk_mul_f32 v[32:33], v[64:65], v[32:33]
	v_mov_b32_e32 v55, v66
	v_mov_b32_e32 v57, v33
	v_pk_add_f32 v[54:55], v[84:85], v[54:55]
	v_pk_add_f32 v[32:33], v[56:57], v[82:83]
	v_mov_b32_e32 v66, v65
	v_pk_add_f32 v[32:33], v[32:33], v[54:55]
	v_lshlrev_b32_e32 v62, 16, v36
	v_add_f32_e32 v32, v32, v33
	ds_bpermute_b32 v33, v206, v32
	v_and_b32_e32 v63, 0xffff0000, v36
	v_lshlrev_b32_e32 v36, 16, v37
	v_and_b32_e32 v37, 0xffff0000, v37
	v_lshl_add_u64 v[2:3], v[2:3], 0, s[4:5]
	s_waitcnt lgkmcnt(0)
	v_add_f32_e32 v32, v32, v33
	ds_bpermute_b32 v33, v207, v32
	s_waitcnt lgkmcnt(0)
	v_add_f32_e32 v32, v32, v33
	ds_bpermute_b32 v33, v208, v32
	s_waitcnt lgkmcnt(0)
	v_add_f32_e32 v32, v32, v33
	ds_bpermute_b32 v33, v209, v32
	s_waitcnt lgkmcnt(0)
	v_add_f32_e32 v32, v32, v33
	ds_bpermute_b32 v33, v210, v32
	s_waitcnt lgkmcnt(0)
	v_add_f32_e32 v32, v32, v33
	ds_bpermute_b32 v33, v211, v32
	s_waitcnt lgkmcnt(0)
; DI unsigned cvt_pk_bf16(float lo, float hi) { const f32x2 v = {lo, hi}; return __builtin_bit_cast(unsigned, __builtin_convertvector(v, bf16x2_t)); }
; DI float bflo(unsigned w) { return __uint_as_float(w << 16); }
; DI float bfhi(unsigned w) { return __uint_as_float(w & 0xffff0000u); }
; template <bool XOUT_BF, int NR>
; DI void norm_rows(const bf16_t* xin, const bf16_t* Rb, const float* gpost, void* xout, const float* gpre, bf16_t* xnb, size_t row0, size_t rstride, int lane) {
;     ...
;         for (int j = 0; j < 4; ++j) { const size_t off = (row0 + q * rstride) * D + 4 * lane + 256 * j;
;             const u32x2 w = __builtin_nontemporal_load((const u32x2*)(xin + off)); v[q][j] = (f32x4){bflo(w.x), bfhi(w.x), bflo(w.y), bfhi(w.y)};
;             const u32x2 w2 = __builtin_nontemporal_load((const u32x2*)(Rb + off)); r[q][j] = (f32x4){bflo(w2.x), bfhi(w2.x), bflo(w2.y), bfhi(w2.y)}; }
;     float ss[NR], s2[NR];
; #pragma unroll
;     for (int q = 0; q < NR; ++q) { ss[q] = 0.f; s2[q] = 0.f;
; #pragma unroll
;         for (int j = 0; j < 4; ++j) ss[q] += (r[q][j][0] * r[q][j][0] + r[q][j][1] * r[q][j][1]) + (r[q][j][2] * r[q][j][2] + r[q][j][3] * r[q][j][3]); }
; #pragma unroll
;     for (int o = 1; o < 64; o <<= 1)
; #pragma unroll
;         for (int q = 0; q < NR; ++q) ss[q] += __shfl_xor(ss[q], o);
; #pragma unroll
;     for (int q = 0; q < NR; ++q) { const float rinv = __builtin_amdgcn_rsqf(ss[q] * (1.f / 1024.f) + EPS);
; #pragma unroll
;         for (int j = 0; j < 4; ++j) { const size_t off = (row0 + q * rstride) * D + 4 * lane + 256 * j;
;             const f32x4 g = *(const f32x4*)(gpost + 4 * lane + 256 * j); v[q][j] += r[q][j] * rinv * g;
;             if (XOUT_BF) { u32x2 w; w.x = cvt_pk_bf16(v[q][j][0], v[q][j][1]); w.y = cvt_pk_bf16(v[q][j][2], v[q][j][3]); __builtin_nontemporal_store(w, (u32x2*)((bf16_t*)xout + off));
;                            v[q][j] = (f32x4){bflo(w.x), bfhi(w.x), bflo(w.y), bfhi(w.y)}; }
;             else *(f32x4*)((float*)xout + off) = v[q][j];
;             s2[q] += (v[q][j][0] * v[q][j][0] + v[q][j][1] * v[q][j][1]) + (v[q][j][2] * v[q][j][2] + v[q][j][3] * v[q][j][3]); } }
	v_add_f32_e32 v32, v32, v33
	v_fmamk_f32 v32, v32, 0x3a800000, v217
	v_rsq_f32_e32 v32, v32
	s_nop 0
	v_pk_mul_f32 v[54:55], v[32:33], v[74:75] op_sel_hi:[0,1]
	v_pk_mul_f32 v[56:57], v[32:33], v[80:81] op_sel_hi:[0,1]
	s_nop 0
	v_mov_b32_e32 v12, v140
	v_mov_b32_e32 v13, v141
	v_mov_b32_e32 v14, v142
	v_mov_b32_e32 v15, v143
	v_pk_fma_f32 v[12:13], v[56:57], v[12:13], v[58:59]
	v_pk_fma_f32 v[14:15], v[54:55], v[14:15], v[60:61]
	global_store_dwordx4 v[20:21], v[12:15], off
	v_mov_b32_e32 v56, v77
	v_mov_b32_e32 v57, v69
	v_mov_b32_e32 v77, v68
	v_lshlrev_b32_e32 v54, 16, v52
	v_and_b32_e32 v55, 0xffff0000, v52
	v_lshlrev_b32_e32 v52, 16, v53
	v_and_b32_e32 v53, 0xffff0000, v53
	v_pk_mul_f32 v[56:57], v[32:33], v[56:57] op_sel_hi:[0,1]
	v_pk_mul_f32 v[58:59], v[32:33], v[76:77] op_sel_hi:[0,1]
	v_lshlrev_b32_e32 v60, 16, v40
	v_and_b32_e32 v61, 0xffff0000, v40
	v_lshlrev_b32_e32 v40, 16, v41
	v_and_b32_e32 v41, 0xffff0000, v41
	s_nop 0
	v_mov_b32_e32 v12, v144
	v_mov_b32_e32 v13, v145
	v_mov_b32_e32 v14, v146
	v_mov_b32_e32 v15, v147
	v_pk_fma_f32 v[12:13], v[58:59], v[12:13], v[54:55]
	v_pk_fma_f32 v[14:15], v[56:57], v[14:15], v[52:53]
	global_store_dwordx4 v[20:21], v[12:15], off offset:1024
	v_lshlrev_b32_e32 v52, 16, v50
	v_and_b32_e32 v53, 0xffff0000, v50
	v_lshlrev_b32_e32 v50, 16, v51
	v_and_b32_e32 v51, 0xffff0000, v51
	v_pk_mul_f32 v[54:55], v[32:33], v[70:71] op_sel_hi:[0,1]
	v_pk_mul_f32 v[56:57], v[32:33], v[78:79] op_sel_hi:[0,1]
	v_lshlrev_b32_e32 v33, 16, v46
	v_pk_mul_f32 v[64:65], v[32:33], v[72:73] op_sel_hi:[0,1]
	v_pk_mul_f32 v[66:67], v[32:33], v[66:67] op_sel_hi:[0,1]
	v_lshlrev_b32_e32 v59, 16, v43
	v_lshlrev_b32_e32 v58, 16, v42
	v_and_b32_e32 v43, 0xffff0000, v43
	v_and_b32_e32 v42, 0xffff0000, v42
	v_mul_f32_e32 v32, v61, v61
	s_nop 0
	v_mov_b32_e32 v12, v148
	v_mov_b32_e32 v13, v149
	v_mov_b32_e32 v14, v150
	v_mov_b32_e32 v15, v151
	v_pk_fma_f32 v[12:13], v[56:57], v[12:13], v[52:53]
	v_pk_fma_f32 v[14:15], v[54:55], v[14:15], v[50:51]
	global_store_dwordx4 v[20:21], v[12:15], off offset:2048
	v_lshlrev_b32_e32 v52, 16, v38
	v_and_b32_e32 v53, 0xffff0000, v38
	v_lshlrev_b32_e32 v38, 16, v39
	v_and_b32_e32 v39, 0xffff0000, v39
	v_and_b32_e32 v57, 0xffff0000, v46
	v_mul_f32_e32 v56, v63, v63
	v_lshl_add_u64 v[50:51], v[20:21], 0, s[50:51]
	v_pk_fma_f32 v[68:69], v[62:63], v[62:63], v[56:57] op_sel_hi:[1,1,0]
	v_lshlrev_b32_e32 v46, 16, v47
	v_and_b32_e32 v47, 0xffff0000, v47
	v_mul_f32_e32 v49, v57, v57
	v_mul_f32_e32 v70, v46, v46
	v_mul_f32_e32 v71, v47, v47
	v_lshlrev_b32_e32 v54, 16, v44
	v_and_b32_e32 v55, 0xffff0000, v44
	v_lshlrev_b32_e32 v44, 16, v45
	v_and_b32_e32 v45, 0xffff0000, v45
	v_mov_b32_e32 v56, v33
	s_nop 0
	v_mov_b32_e32 v12, v152
	v_mov_b32_e32 v13, v153
	v_mov_b32_e32 v14, v154
	v_mov_b32_e32 v15, v155
	v_pk_fma_f32 v[12:13], v[66:67], v[12:13], v[52:53]
	v_pk_fma_f32 v[14:15], v[64:65], v[14:15], v[38:39]
	global_store_dwordx4 v[20:21], v[12:15], off offset:3072
	v_mul_f32_e32 v52, v37, v37
	v_pk_mul_f32 v[20:21], v[42:43], v[42:43]
	v_mov_b32_e32 v39, v33
	v_mul_f32_e32 v38, v41, v41
	v_pk_fma_f32 v[52:53], v[36:37], v[36:37], v[52:53] op_sel_hi:[1,1,0]
	v_pk_fma_f32 v[20:21], v[58:59], v[58:59], v[20:21]
	v_pk_fma_f32 v[64:65], v[60:61], v[60:61], v[32:33] op_sel_hi:[1,1,0]
	v_pk_fma_f32 v[66:67], v[40:41], v[40:41], v[38:39] op_sel_hi:[1,1,0]
	v_mov_b32_e32 v32, v68
	v_mov_b32_e32 v38, v52
	v_pk_add_f32 v[20:21], v[20:21], v[20:21] op_sel:[0,1] op_sel_hi:[1,0]
	v_pk_add_f32 v[52:53], v[68:69], v[52:53]
	v_pk_mul_f32 v[38:39], v[32:33], v[38:39]
	v_mov_b32_e32 v65, v70
	v_mov_b32_e32 v67, v71
	v_mov_b32_e32 v21, v49
	v_mov_b32_e32 v53, v39
	v_pk_add_f32 v[64:65], v[64:65], v[66:67]
	v_pk_add_f32 v[20:21], v[52:53], v[20:21]
	v_and_b32_e32 v33, 0xffff0000, v28
	v_pk_add_f32 v[20:21], v[20:21], v[64:65]
	v_mul_f32_e32 v49, v33, v33
	v_add_f32_e32 v20, v20, v21
	ds_bpermute_b32 v21, v206, v20
	s_waitcnt lgkmcnt(0)
	v_add_f32_e32 v20, v20, v21
	ds_bpermute_b32 v21, v207, v20
	s_waitcnt lgkmcnt(0)
	v_add_f32_e32 v20, v20, v21
	ds_bpermute_b32 v21, v208, v20
	s_waitcnt lgkmcnt(0)
	v_add_f32_e32 v20, v20, v21
	ds_bpermute_b32 v21, v209, v20
	s_waitcnt lgkmcnt(0)
	v_add_f32_e32 v20, v20, v21
	ds_bpermute_b32 v21, v210, v20
	s_waitcnt lgkmcnt(0)
	v_add_f32_e32 v20, v20, v21
	ds_bpermute_b32 v21, v211, v20
	s_waitcnt lgkmcnt(0)
; DI unsigned cvt_pk_bf16(float lo, float hi) { const f32x2 v = {lo, hi}; return __builtin_bit_cast(unsigned, __builtin_convertvector(v, bf16x2_t)); }
; DI float bflo(unsigned w) { return __uint_as_float(w << 16); }
; DI float bfhi(unsigned w) { return __uint_as_float(w & 0xffff0000u); }
; template <bool XOUT_BF, int NR>
; DI void norm_rows(const bf16_t* xin, const bf16_t* Rb, const float* gpost, void* xout, const float* gpre, bf16_t* xnb, size_t row0, size_t rstride, int lane) {
;     ...
;         for (int j = 0; j < 4; ++j) { const size_t off = (row0 + q * rstride) * D + 4 * lane + 256 * j;
;             const u32x2 w = __builtin_nontemporal_load((const u32x2*)(xin + off)); v[q][j] = (f32x4){bflo(w.x), bfhi(w.x), bflo(w.y), bfhi(w.y)};
;             const u32x2 w2 = __builtin_nontemporal_load((const u32x2*)(Rb + off)); r[q][j] = (f32x4){bflo(w2.x), bfhi(w2.x), bflo(w2.y), bfhi(w2.y)}; }
;     float ss[NR], s2[NR];
; #pragma unroll
;     for (int q = 0; q < NR; ++q) { ss[q] = 0.f; s2[q] = 0.f;
; #pragma unroll
;         for (int j = 0; j < 4; ++j) ss[q] += (r[q][j][0] * r[q][j][0] + r[q][j][1] * r[q][j][1]) + (r[q][j][2] * r[q][j][2] + r[q][j][3] * r[q][j][3]); }
; #pragma unroll
;     for (int o = 1; o < 64; o <<= 1)
; #pragma unroll
;         for (int q = 0; q < NR; ++q) ss[q] += __shfl_xor(ss[q], o);
; #pragma unroll
;     for (int q = 0; q < NR; ++q) { const float rinv = __builtin_amdgcn_rsqf(ss[q] * (1.f / 1024.f) + EPS);
; #pragma unroll
;         for (int j = 0; j < 4; ++j) { const size_t off = (row0 + q * rstride) * D + 4 * lane + 256 * j;
;             const f32x4 g = *(const f32x4*)(gpost + 4 * lane + 256 * j); v[q][j] += r[q][j] * rinv * g;
;             if (XOUT_BF) { u32x2 w; w.x = cvt_pk_bf16(v[q][j][0], v[q][j][1]); w.y = cvt_pk_bf16(v[q][j][2], v[q][j][3]); __builtin_nontemporal_store(w, (u32x2*)((bf16_t*)xout + off));
;                            v[q][j] = (f32x4){bflo(w.x), bfhi(w.x), bflo(w.y), bfhi(w.y)}; }
;             else *(f32x4*)((float*)xout + off) = v[q][j];
;             s2[q] += (v[q][j][0] * v[q][j][0] + v[q][j][1] * v[q][j][1]) + (v[q][j][2] * v[q][j][2] + v[q][j][3] * v[q][j][3]); } }
	v_add_f32_e32 v20, v20, v21
	v_fmamk_f32 v20, v20, 0x3a800000, v217
	v_rsq_f32_e32 v20, v20
	s_nop 0
	v_pk_mul_f32 v[36:37], v[20:21], v[36:37] op_sel_hi:[0,1]
	v_pk_mul_f32 v[38:39], v[20:21], v[62:63] op_sel_hi:[0,1]
	s_nop 0
	v_mov_b32_e32 v12, v140
	v_mov_b32_e32 v13, v141
	v_mov_b32_e32 v14, v142
	v_mov_b32_e32 v15, v143
	v_pk_fma_f32 v[12:13], v[38:39], v[12:13], v[54:55]
	v_pk_fma_f32 v[14:15], v[36:37], v[14:15], v[44:45]
	global_store_dwordx4 v[50:51], v[12:15], off
	v_mov_b32_e32 v38, v59
	v_mov_b32_e32 v39, v43
	v_mov_b32_e32 v59, v42
	v_lshlrev_b32_e32 v36, 16, v34
	v_and_b32_e32 v37, 0xffff0000, v34
	v_lshlrev_b32_e32 v34, 16, v35
	v_and_b32_e32 v35, 0xffff0000, v35
	v_pk_mul_f32 v[38:39], v[20:21], v[38:39] op_sel_hi:[0,1]
	v_pk_mul_f32 v[42:43], v[20:21], v[58:59] op_sel_hi:[0,1]
	s_nop 0
	v_mov_b32_e32 v12, v144
	v_mov_b32_e32 v13, v145
	v_mov_b32_e32 v14, v146
	v_mov_b32_e32 v15, v147
	v_pk_fma_f32 v[12:13], v[42:43], v[12:13], v[36:37]
	v_pk_fma_f32 v[14:15], v[38:39], v[14:15], v[34:35]
	global_store_dwordx4 v[50:51], v[12:15], off offset:1024
	v_lshlrev_b32_e32 v34, 16, v30
	v_and_b32_e32 v35, 0xffff0000, v30
	v_lshlrev_b32_e32 v30, 16, v31
	v_and_b32_e32 v31, 0xffff0000, v31
	v_pk_mul_f32 v[36:37], v[20:21], v[40:41] op_sel_hi:[0,1]
	v_pk_mul_f32 v[38:39], v[20:21], v[60:61] op_sel_hi:[0,1]
	v_lshlrev_b32_e32 v21, 16, v28
	v_pk_mul_f32 v[42:43], v[20:21], v[46:47] op_sel_hi:[0,1]
	v_pk_mul_f32 v[44:45], v[20:21], v[56:57] op_sel_hi:[0,1]
	v_and_b32_e32 v41, 0xffff0000, v18
	v_lshlrev_b32_e32 v40, 16, v18
	v_lshlrev_b32_e32 v18, 16, v19
	v_and_b32_e32 v19, 0xffff0000, v19
	v_mul_f32_e32 v20, v41, v41
	v_lshlrev_b32_e32 v28, 16, v29
	v_and_b32_e32 v29, 0xffff0000, v29
	v_mul_f32_e32 v32, v19, v19
	v_pk_fma_f32 v[46:47], v[40:41], v[40:41], v[20:21] op_sel_hi:[1,1,0]
	v_mul_f32_e32 v54, v28, v28
	v_mul_f32_e32 v55, v29, v29
	v_mov_b32_e32 v47, v54
	s_nop 0
	v_mov_b32_e32 v12, v148
	v_mov_b32_e32 v13, v149
	v_mov_b32_e32 v14, v150
	v_mov_b32_e32 v15, v151
	v_pk_fma_f32 v[12:13], v[38:39], v[12:13], v[34:35]
	v_pk_fma_f32 v[14:15], v[36:37], v[14:15], v[30:31]
	global_store_dwordx4 v[50:51], v[12:15], off offset:2048
	v_lshlrev_b32_e32 v34, 16, v24
	v_and_b32_e32 v35, 0xffff0000, v24
	v_lshlrev_b32_e32 v24, 16, v25
	v_and_b32_e32 v25, 0xffff0000, v25
	v_lshlrev_b32_e32 v39, 16, v23
	v_lshlrev_b32_e32 v38, 16, v22
	v_and_b32_e32 v23, 0xffff0000, v23
	v_and_b32_e32 v22, 0xffff0000, v22
	v_lshl_add_u64 v[30:31], v[50:51], 0, s[50:51]
	v_lshlrev_b32_e32 v36, 16, v26
	v_and_b32_e32 v37, 0xffff0000, v26
	v_lshlrev_b32_e32 v26, 16, v27
	v_and_b32_e32 v27, 0xffff0000, v27
	s_nop 0
	v_mov_b32_e32 v12, v152
	v_mov_b32_e32 v13, v153
	v_mov_b32_e32 v14, v154
	v_mov_b32_e32 v15, v155
	v_pk_fma_f32 v[12:13], v[44:45], v[12:13], v[34:35]
	v_pk_fma_f32 v[14:15], v[42:43], v[14:15], v[24:25]
	global_store_dwordx4 v[50:51], v[12:15], off offset:3072
	v_lshlrev_b32_e32 v24, 16, v16
	v_and_b32_e32 v25, 0xffff0000, v16
	v_lshlrev_b32_e32 v16, 16, v17
	v_and_b32_e32 v17, 0xffff0000, v17
	v_mov_b32_e32 v43, v21
	v_mul_f32_e32 v42, v17, v17
	v_mul_f32_e32 v44, v25, v25
	v_pk_mul_f32 v[34:35], v[22:23], v[22:23]
	v_pk_fma_f32 v[52:53], v[16:17], v[16:17], v[42:43] op_sel_hi:[1,1,0]
	v_pk_fma_f32 v[44:45], v[24:25], v[24:25], v[44:45] op_sel_hi:[1,1,0]
	v_pk_fma_f32 v[34:35], v[38:39], v[38:39], v[34:35]
	v_mov_b32_e32 v20, v44
	v_mov_b32_e32 v42, v52
	v_pk_fma_f32 v[50:51], v[18:19], v[18:19], v[32:33] op_sel_hi:[1,1,0]
	v_pk_add_f32 v[34:35], v[34:35], v[34:35] op_sel:[0,1] op_sel_hi:[1,0]
	v_pk_add_f32 v[44:45], v[44:45], v[52:53]
	v_pk_mul_f32 v[42:43], v[20:21], v[42:43]
	v_mov_b32_e32 v51, v55
	v_mov_b32_e32 v35, v49
	v_mov_b32_e32 v45, v43
	v_pk_add_f32 v[46:47], v[46:47], v[50:51]
	v_pk_add_f32 v[34:35], v[44:45], v[34:35]
	s_nop 0
	v_pk_add_f32 v[34:35], v[34:35], v[46:47]
	s_nop 0
	v_add_f32_e32 v20, v34, v35
	ds_bpermute_b32 v32, v206, v20
	s_waitcnt lgkmcnt(0)
	v_add_f32_e32 v20, v20, v32
	ds_bpermute_b32 v32, v207, v20
	s_waitcnt lgkmcnt(0)
	v_add_f32_e32 v20, v20, v32
	ds_bpermute_b32 v32, v208, v20
	s_waitcnt lgkmcnt(0)
	v_add_f32_e32 v20, v20, v32
	ds_bpermute_b32 v32, v209, v20
	s_waitcnt lgkmcnt(0)
	v_add_f32_e32 v20, v20, v32
	ds_bpermute_b32 v32, v210, v20
	s_waitcnt lgkmcnt(0)
	v_add_f32_e32 v20, v20, v32
	ds_bpermute_b32 v32, v211, v20
	s_waitcnt lgkmcnt(0)
	v_add_f32_e32 v20, v20, v32
	v_fmamk_f32 v20, v20, 0x3a800000, v217
	v_rsq_f32_e32 v20, v20
	v_mov_b32_e32 v32, v21
	v_pk_mul_f32 v[16:17], v[20:21], v[16:17] op_sel_hi:[0,1]
	v_pk_mul_f32 v[24:25], v[20:21], v[24:25] op_sel_hi:[0,1]
	v_pk_mul_f32 v[18:19], v[20:21], v[18:19] op_sel_hi:[0,1]
	s_nop 0
	v_mov_b32_e32 v12, v140
	v_mov_b32_e32 v13, v141
	v_mov_b32_e32 v14, v142
	v_mov_b32_e32 v15, v143
	v_pk_fma_f32 v[12:13], v[24:25], v[12:13], v[36:37]
	v_pk_fma_f32 v[14:15], v[16:17], v[14:15], v[26:27]
	global_store_dwordx4 v[30:31], v[12:15], off
	v_lshlrev_b32_e32 v16, 16, v10
	v_and_b32_e32 v17, 0xffff0000, v10
	v_lshlrev_b32_e32 v24, 16, v11
	v_and_b32_e32 v25, 0xffff0000, v11
	v_mov_b32_e32 v10, v39
	v_mov_b32_e32 v11, v23
	v_mov_b32_e32 v39, v22
	v_pk_mul_f32 v[22:23], v[20:21], v[10:11] op_sel_hi:[0,1]
	v_pk_mul_f32 v[10:11], v[20:21], v[38:39] op_sel_hi:[0,1]
	s_nop 0
	v_mov_b32_e32 v12, v144
	v_mov_b32_e32 v13, v145
	v_mov_b32_e32 v14, v146
	v_mov_b32_e32 v15, v147
	v_pk_fma_f32 v[10:11], v[10:11], v[12:13], v[16:17]
	v_pk_fma_f32 v[12:13], v[22:23], v[14:15], v[24:25]
	global_store_dwordx4 v[30:31], v[10:13], off offset:1024
	v_lshlrev_b32_e32 v14, 16, v8
	v_and_b32_e32 v15, 0xffff0000, v8
	v_lshlrev_b32_e32 v16, 16, v9
	v_and_b32_e32 v17, 0xffff0000, v9
	v_pk_mul_f32 v[8:9], v[20:21], v[40:41] op_sel_hi:[0,1]
	s_nop 0
	v_mov_b32_e32 v10, v148
	v_mov_b32_e32 v11, v149
	v_mov_b32_e32 v12, v150
	v_mov_b32_e32 v13, v151
	v_pk_fma_f32 v[8:9], v[8:9], v[10:11], v[14:15]
	v_pk_fma_f32 v[10:11], v[18:19], v[12:13], v[16:17]
	global_store_dwordx4 v[30:31], v[8:11], off offset:2048
	v_lshlrev_b32_e32 v12, 16, v6
	v_and_b32_e32 v13, 0xffff0000, v6
	v_lshlrev_b32_e32 v14, 16, v7
	v_and_b32_e32 v15, 0xffff0000, v7
	v_pk_mul_f32 v[16:17], v[20:21], v[28:29] op_sel_hi:[0,1]
	v_pk_mul_f32 v[6:7], v[20:21], v[32:33] op_sel_hi:[0,1]
	s_nop 0
	v_mov_b32_e32 v8, v152
	v_mov_b32_e32 v9, v153
	v_mov_b32_e32 v10, v154
	v_mov_b32_e32 v11, v155
	v_pk_fma_f32 v[6:7], v[6:7], v[8:9], v[12:13]
	v_pk_fma_f32 v[8:9], v[16:17], v[10:11], v[14:15]
	global_store_dwordx4 v[30:31], v[6:9], off offset:3072
	s_cbranch_scc0 .LBB0_1593
